# first K-loop wait of every tile relaxed by the number of VMEM ops the previous epilogue always issues (P1, P4, P5)
# speedup vs baseline: 1.0096x; 1.0016x over previous
; #define PG8_STAGE(bufoff, gbase, voff) do { _Pragma("unroll") for (int _i = 0; _i < 2; ++_i) \
;         __builtin_amdgcn_global_load_lds((const unsigned*)((const char*)(gbase) + (voff)[_i]), (LAS unsigned*)(lds + (bufoff) + ldsw + _i * 8192), 16, 0, 0); } while (0)
; #define PG8_LDA(dst, b, h) do { _Pragma("unroll") for (int m = 0; m < 4; ++m) _Pragma("unroll") for (int k = 0; k < 2; ++k) dst[m][k] = *(const LAS bf16x8*)(lds + PG8_SA(b, h) + aoff + m * 2048 + k * 1024); } while (0)
; #define PG8_LDB(dst, b, h) do { _Pragma("unroll") for (int n = 0; n < 2; ++n) _Pragma("unroll") for (int k = 0; k < 2; ++k) dst[n][k] = *(const LAS bf16x8*)(lds + PG8_SB(b, h) + boff + n * 2048 + k * 1024); } while (0)
; #define PG8_MMA(ai, bj, At, Bt) do { __builtin_amdgcn_s_setprio(1); _Pragma("unroll") for (int m = 0; m < 4; ++m) _Pragma("unroll") for (int n = 0; n < 2; ++n) _Pragma("unroll") for (int k = 0; k < 2; ++k) \
;         acc[ai][bj][m][n] = __builtin_amdgcn_mfma_f32_16x16x32_bf16(Bt[n][k], At[m][k], acc[ai][bj][m][n], 0, 0, 0); __builtin_amdgcn_s_setprio(0); } while (0)
; #define PG8_WAIT_V(n) asm volatile("s_waitcnt vmcnt(" #n ")" ::: "memory")
; #define PG8_WAIT_L(n) asm volatile("s_waitcnt lgkmcnt(" #n ")" ::: "memory")
; #define PG8_BAR __builtin_amdgcn_s_barrier()
; #define PG8_SCHED __builtin_amdgcn_sched_barrier(0)
; template <class Epi, int AC0, int BC0, int NT0, int AC1, int BC1, int NT1>
; __device__ __forceinline__ void gemm_phase(LAS unsigned char* lds, const Gemm g, const StaticOrder& S, const Epi& E, int tid) {
;     ...
;             PG8_LDB(B0, 0, 0); PG8_LDB(B1, 0, 1); PG8_SCHED; PG8_LDA(At, 0, 0); PG8_STAGE(PG8_SA(1, 1), a1 + hstepA, voffA);
;             PG8_WAIT_V(8); PG8_WAIT_L(0); PG8_BAR; PG8_MMA(0, 0, At, B0); PG8_MMA(0, 1, At, B1); PG8_BAR; PG8_SCHED;
;             PG8_LDA(At, 0, 1); PG8_STAGE(PG8_SB(0, 0), b2, voffB); PG8_STAGE(PG8_SB(0, 1), b2 + hstepB, voffB); PG8_STAGE(PG8_SA(0, 0), a2, voffA);
;             PG8_WAIT_V(8); PG8_WAIT_L(0); PG8_BAR; PG8_MMA(1, 0, At, B0); PG8_MMA(1, 1, At, B1); PG8_BAR; PG8_SCHED;
.Lpeel_P1:
	ds_read_b128 v[26:29], v192
	ds_read_b128 v[30:33], v192 offset:1024
	ds_read_b128 v[42:45], v192 offset:2048
	ds_read_b128 v[46:49], v192 offset:3072
	ds_read_b128 v[146:149], v193
	ds_read_b128 v[150:153], v193 offset:1024
	ds_read_b128 v[154:157], v193 offset:2048
	ds_read_b128 v[158:161], v193 offset:3072
	s_add_u32 s6, s0, 0xfffc0080
	s_addc_u32 s7, s1, -1
	s_cmp_eq_u32 s27, 12
	s_cselect_b32 s13, s3, s7
	s_cselect_b32 s12, s9, s6
	s_cselect_b32 s7, s11, s22
	s_cselect_b32 s6, s15, s16
	v_lshl_add_u64 v[186:187], s[0:1], 0, v[178:179]
	s_add_i32 m0, s95, 0xc000
	ds_read_b128 v[198:201], v194
	ds_read_b128 v[202:205], v194 offset:1024
	ds_read_b128 v[206:209], v194 offset:2048
	ds_read_b128 v[210:213], v194 offset:3072
	ds_read_b128 v[214:217], v194 offset:4096
	ds_read_b128 v[218:221], v194 offset:5120
	ds_read_b128 v[226:229], v194 offset:6144
	ds_read_b128 v[230:233], v194 offset:7168
	global_load_lds_dwordx4 v[186:187], off
	v_lshl_add_u64 v[186:187], s[0:1], 0, v[180:181]
	s_add_i32 m0, s95, 0xe000
	s_nop 0
	global_load_lds_dwordx4 v[186:187], off
	s_waitcnt vmcnt(24)
	s_waitcnt lgkmcnt(0)
	s_barrier
	s_setprio 1
	s_waitcnt lgkmcnt(0)
	v_mfma_f32_16x16x32_bf16 v[142:145], v[26:29], v[198:201], 0
	v_mfma_f32_16x16x32_bf16 v[138:141], v[42:45], v[198:201], 0
	v_mfma_f32_16x16x32_bf16 v[126:129], v[26:29], v[206:209], 0
	v_mfma_f32_16x16x32_bf16 v[122:125], v[42:45], v[206:209], 0
	v_mfma_f32_16x16x32_bf16 v[110:113], v[26:29], v[214:217], 0
	v_mfma_f32_16x16x32_bf16 v[106:109], v[42:45], v[214:217], 0
	v_mfma_f32_16x16x32_bf16 v[94:97], v[26:29], v[226:229], 0
	v_mfma_f32_16x16x32_bf16 v[90:93], v[42:45], v[226:229], 0
	v_mfma_f32_16x16x32_bf16 v[142:145], v[30:33], v[202:205], v[142:145]
	v_mfma_f32_16x16x32_bf16 v[138:141], v[46:49], v[202:205], v[138:141]
	v_mfma_f32_16x16x32_bf16 v[126:129], v[30:33], v[210:213], v[126:129]
	v_mfma_f32_16x16x32_bf16 v[122:125], v[46:49], v[210:213], v[122:125]
	v_mfma_f32_16x16x32_bf16 v[110:113], v[30:33], v[218:221], v[110:113]
	v_mfma_f32_16x16x32_bf16 v[106:109], v[46:49], v[218:221], v[106:109]
	v_mfma_f32_16x16x32_bf16 v[94:97], v[30:33], v[230:233], v[94:97]
	v_mfma_f32_16x16x32_bf16 v[90:93], v[46:49], v[230:233], v[90:93]
	s_setprio 0
	s_setprio 1
	v_mfma_f32_16x16x32_bf16 v[134:137], v[146:149], v[198:201], 0
	v_mfma_f32_16x16x32_bf16 v[130:133], v[154:157], v[198:201], 0
	v_mfma_f32_16x16x32_bf16 v[118:121], v[146:149], v[206:209], 0
	v_mfma_f32_16x16x32_bf16 v[114:117], v[154:157], v[206:209], 0
	v_mfma_f32_16x16x32_bf16 v[102:105], v[146:149], v[214:217], 0
	v_mfma_f32_16x16x32_bf16 v[98:101], v[154:157], v[214:217], 0
	v_mfma_f32_16x16x32_bf16 v[86:89], v[146:149], v[226:229], 0
	v_mfma_f32_16x16x32_bf16 v[82:85], v[154:157], v[226:229], 0
	v_mfma_f32_16x16x32_bf16 v[134:137], v[150:153], v[202:205], v[134:137]
	v_mfma_f32_16x16x32_bf16 v[130:133], v[158:161], v[202:205], v[130:133]
	v_mfma_f32_16x16x32_bf16 v[118:121], v[150:153], v[210:213], v[118:121]
	v_mfma_f32_16x16x32_bf16 v[114:117], v[158:161], v[210:213], v[114:117]
	v_mfma_f32_16x16x32_bf16 v[102:105], v[150:153], v[218:221], v[102:105]
	v_mfma_f32_16x16x32_bf16 v[98:101], v[158:161], v[218:221], v[98:101]
	v_mfma_f32_16x16x32_bf16 v[86:89], v[150:153], v[230:233], v[86:89]
	v_mfma_f32_16x16x32_bf16 v[82:85], v[158:161], v[230:233], v[82:85]
	s_setprio 0
	s_barrier
	s_add_i32 s29, s94, s47
	v_lshl_add_u64 v[186:187], s[6:7], 0, v[166:167]
	s_mov_b32 m0, s29
	ds_read_b128 v[198:201], v194 offset:16384
	ds_read_b128 v[202:205], v194 offset:17408
	ds_read_b128 v[206:209], v194 offset:18432
	ds_read_b128 v[210:213], v194 offset:19456
	ds_read_b128 v[214:217], v194 offset:20480
	ds_read_b128 v[218:221], v194 offset:21504
	ds_read_b128 v[226:229], v194 offset:22528
	ds_read_b128 v[230:233], v194 offset:23552
	global_load_lds_dwordx4 v[186:187], off
	s_add_i32 m0, s29, 0x2000
	s_add_u32 s36, s6, 0x40000
	v_lshl_add_u64 v[222:223], s[6:7], 0, v[170:171]
	s_addc_u32 s37, s7, 0
	s_add_i32 s29, s18, s47
	global_load_lds_dwordx4 v[222:223], off
	v_lshl_add_u64 v[234:235], s[36:37], 0, v[166:167]
	s_mov_b32 m0, s29
	v_lshl_add_u64 v[236:237], s[12:13], 0, v[168:169]
	global_load_lds_dwordx4 v[234:235], off
	v_lshl_add_u64 v[234:235], s[36:37], 0, v[170:171]
	s_add_i32 m0, s29, 0x2000
	s_nop 0
	global_load_lds_dwordx4 v[234:235], off
	v_lshl_add_u64 v[234:235], s[12:13], 0, v[164:165]
	s_mov_b32 m0, s95
	s_nop 0
	global_load_lds_dwordx4 v[234:235], off
	s_mov_b32 m0, s96
	s_nop 0
	global_load_lds_dwordx4 v[236:237], off
	s_waitcnt vmcnt(8)
	s_waitcnt lgkmcnt(0)
	s_barrier
	s_setprio 1
	s_waitcnt lgkmcnt(0)
	v_mfma_f32_16x16x32_bf16 v[78:81], v[26:29], v[198:201], 0
	v_mfma_f32_16x16x32_bf16 v[74:77], v[42:45], v[198:201], 0
	v_mfma_f32_16x16x32_bf16 v[62:65], v[26:29], v[206:209], 0
	v_mfma_f32_16x16x32_bf16 v[58:61], v[42:45], v[206:209], 0
	v_mfma_f32_16x16x32_bf16 v[38:41], v[26:29], v[214:217], 0
	v_mfma_f32_16x16x32_bf16 v[34:37], v[42:45], v[214:217], 0
	v_mfma_f32_16x16x32_bf16 v[14:17], v[26:29], v[226:229], 0
	v_mfma_f32_16x16x32_bf16 v[10:13], v[42:45], v[226:229], 0
	v_mfma_f32_16x16x32_bf16 v[78:81], v[30:33], v[202:205], v[78:81]
	v_mfma_f32_16x16x32_bf16 v[74:77], v[46:49], v[202:205], v[74:77]
	v_mfma_f32_16x16x32_bf16 v[62:65], v[30:33], v[210:213], v[62:65]
	v_mfma_f32_16x16x32_bf16 v[58:61], v[46:49], v[210:213], v[58:61]
	v_mfma_f32_16x16x32_bf16 v[38:41], v[30:33], v[218:221], v[38:41]
	v_mfma_f32_16x16x32_bf16 v[34:37], v[46:49], v[218:221], v[34:37]
	v_mfma_f32_16x16x32_bf16 v[14:17], v[30:33], v[230:233], v[14:17]
	v_mfma_f32_16x16x32_bf16 v[10:13], v[46:49], v[230:233], v[10:13]
	s_setprio 0
	s_setprio 1
	v_mfma_f32_16x16x32_bf16 v[22:25], v[146:149], v[214:217], 0
	v_mfma_f32_16x16x32_bf16 v[18:21], v[154:157], v[214:217], 0
	v_mfma_f32_16x16x32_bf16 v[6:9], v[146:149], v[226:229], 0
	v_mfma_f32_16x16x32_bf16 v[2:5], v[154:157], v[226:229], 0
	v_mfma_f32_16x16x32_bf16 v[26:29], v[146:149], v[198:201], 0
	v_mfma_f32_16x16x32_bf16 v[30:33], v[154:157], v[198:201], 0
	v_mfma_f32_16x16x32_bf16 v[42:45], v[146:149], v[206:209], 0
	v_mfma_f32_16x16x32_bf16 v[46:49], v[154:157], v[206:209], 0
	v_mfma_f32_16x16x32_bf16 v[22:25], v[150:153], v[218:221], v[22:25]
	v_mfma_f32_16x16x32_bf16 v[18:21], v[158:161], v[218:221], v[18:21]
	v_mfma_f32_16x16x32_bf16 v[6:9], v[150:153], v[230:233], v[6:9]
	v_mfma_f32_16x16x32_bf16 v[2:5], v[158:161], v[230:233], v[2:5]
	v_mfma_f32_16x16x32_bf16 v[26:29], v[150:153], v[202:205], v[26:29]
	v_mfma_f32_16x16x32_bf16 v[30:33], v[158:161], v[202:205], v[30:33]
	v_mfma_f32_16x16x32_bf16 v[42:45], v[150:153], v[210:213], v[42:45]
	v_mfma_f32_16x16x32_bf16 v[46:49], v[158:161], v[210:213], v[46:49]
	s_setprio 0
	s_barrier
	s_branch .Lmid_P1

; #define PG8_STAGE(bufoff, gbase, voff) do { _Pragma("unroll") for (int _i = 0; _i < 2; ++_i) \
;         __builtin_amdgcn_global_load_lds((const unsigned*)((const char*)(gbase) + (voff)[_i]), (LAS unsigned*)(lds + (bufoff) + ldsw + _i * 8192), 16, 0, 0); } while (0)
; #define PG8_LDA(dst, b, h) do { _Pragma("unroll") for (int m = 0; m < 4; ++m) _Pragma("unroll") for (int k = 0; k < 2; ++k) dst[m][k] = *(const LAS bf16x8*)(lds + PG8_SA(b, h) + aoff + m * 2048 + k * 1024); } while (0)
; #define PG8_LDB(dst, b, h) do { _Pragma("unroll") for (int n = 0; n < 2; ++n) _Pragma("unroll") for (int k = 0; k < 2; ++k) dst[n][k] = *(const LAS bf16x8*)(lds + PG8_SB(b, h) + boff + n * 2048 + k * 1024); } while (0)
; #define PG8_MMA(ai, bj, At, Bt) do { __builtin_amdgcn_s_setprio(1); _Pragma("unroll") for (int m = 0; m < 4; ++m) _Pragma("unroll") for (int n = 0; n < 2; ++n) _Pragma("unroll") for (int k = 0; k < 2; ++k) \
;         acc[ai][bj][m][n] = __builtin_amdgcn_mfma_f32_16x16x32_bf16(Bt[n][k], At[m][k], acc[ai][bj][m][n], 0, 0, 0); __builtin_amdgcn_s_setprio(0); } while (0)
; #define PG8_WAIT_V(n) asm volatile("s_waitcnt vmcnt(" #n ")" ::: "memory")
; #define PG8_WAIT_L(n) asm volatile("s_waitcnt lgkmcnt(" #n ")" ::: "memory")
; #define PG8_BAR __builtin_amdgcn_s_barrier()
; #define PG8_SCHED __builtin_amdgcn_sched_barrier(0)
; template <class Epi, int AC0, int BC0, int NT0, int AC1, int BC1, int NT1>
; __device__ __forceinline__ void gemm_phase(LAS unsigned char* lds, const Gemm g, const StaticOrder& S, const Epi& E, int tid) {
;     ...
;             PG8_LDB(B0, 0, 0); PG8_LDB(B1, 0, 1); PG8_SCHED; PG8_LDA(At, 0, 0); PG8_STAGE(PG8_SA(1, 1), a1 + hstepA, voffA);
;             PG8_WAIT_V(8); PG8_WAIT_L(0); PG8_BAR; PG8_MMA(0, 0, At, B0); PG8_MMA(0, 1, At, B1); PG8_BAR; PG8_SCHED;
;             PG8_LDA(At, 0, 1); PG8_STAGE(PG8_SB(0, 0), b2, voffB); PG8_STAGE(PG8_SB(0, 1), b2 + hstepB, voffB); PG8_STAGE(PG8_SA(0, 0), a2, voffA);
;             PG8_WAIT_V(8); PG8_WAIT_L(0); PG8_BAR; PG8_MMA(1, 0, At, B0); PG8_MMA(1, 1, At, B1); PG8_BAR; PG8_SCHED;
.Lpeel_P4:
	ds_read_b128 v[130:133], v218
	ds_read_b128 v[134:137], v218 offset:1024
	ds_read_b128 v[138:141], v218 offset:2048
	ds_read_b128 v[142:145], v218 offset:3072
	ds_read_b128 v[146:149], v219
	ds_read_b128 v[150:153], v219 offset:1024
	ds_read_b128 v[154:157], v219 offset:2048
	ds_read_b128 v[158:161], v219 offset:3072
	s_add_u32 s20, s18, 0xfffc0080
	s_addc_u32 s21, s19, -1
	s_cmp_eq_u32 s73, 12
	s_cselect_b32 s67, s0, s21
	s_cselect_b32 s66, s2, s20
	s_cselect_b32 s21, s3, s33
	s_cselect_b32 s20, s13, s15
	v_lshl_add_u64 v[212:213], s[18:19], 0, v[198:199]
	s_add_i32 m0, s26, 0xc000
	ds_read_b128 v[162:165], v220
	ds_read_b128 v[166:169], v220 offset:1024
	ds_read_b128 v[170:173], v220 offset:2048
	ds_read_b128 v[174:177], v220 offset:3072
	ds_read_b128 v[178:181], v220 offset:4096
	ds_read_b128 v[182:185], v220 offset:5120
	ds_read_b128 v[204:207], v220 offset:6144
	ds_read_b128 v[208:211], v220 offset:7168
	global_load_lds_dwordx4 v[212:213], off
	v_lshl_add_u64 v[212:213], s[18:19], 0, v[200:201]
	s_add_i32 m0, s26, 0xe000
	s_nop 0
	global_load_lds_dwordx4 v[212:213], off
	s_waitcnt vmcnt(56)
	s_waitcnt lgkmcnt(0)
	s_barrier
	s_setprio 1
	s_waitcnt lgkmcnt(0)
	v_mfma_f32_16x16x32_bf16 v[126:129], v[130:133], v[162:165], 0
	v_mfma_f32_16x16x32_bf16 v[122:125], v[138:141], v[162:165], 0
	v_mfma_f32_16x16x32_bf16 v[110:113], v[130:133], v[170:173], 0
	v_mfma_f32_16x16x32_bf16 v[106:109], v[138:141], v[170:173], 0
	v_mfma_f32_16x16x32_bf16 v[94:97], v[130:133], v[178:181], 0
	v_mfma_f32_16x16x32_bf16 v[90:93], v[138:141], v[178:181], 0
	v_mfma_f32_16x16x32_bf16 v[78:81], v[130:133], v[204:207], 0
	v_mfma_f32_16x16x32_bf16 v[74:77], v[138:141], v[204:207], 0
	v_mfma_f32_16x16x32_bf16 v[126:129], v[134:137], v[166:169], v[126:129]
	v_mfma_f32_16x16x32_bf16 v[122:125], v[142:145], v[166:169], v[122:125]
	v_mfma_f32_16x16x32_bf16 v[110:113], v[134:137], v[174:177], v[110:113]
	v_mfma_f32_16x16x32_bf16 v[106:109], v[142:145], v[174:177], v[106:109]
	v_mfma_f32_16x16x32_bf16 v[94:97], v[134:137], v[182:185], v[94:97]
	v_mfma_f32_16x16x32_bf16 v[90:93], v[142:145], v[182:185], v[90:93]
	v_mfma_f32_16x16x32_bf16 v[78:81], v[134:137], v[208:211], v[78:81]
	v_mfma_f32_16x16x32_bf16 v[74:77], v[142:145], v[208:211], v[74:77]
	s_setprio 0
	s_setprio 1
	v_mfma_f32_16x16x32_bf16 v[118:121], v[146:149], v[162:165], 0
	v_mfma_f32_16x16x32_bf16 v[114:117], v[154:157], v[162:165], 0
	v_mfma_f32_16x16x32_bf16 v[102:105], v[146:149], v[170:173], 0
	v_mfma_f32_16x16x32_bf16 v[98:101], v[154:157], v[170:173], 0
	v_mfma_f32_16x16x32_bf16 v[86:89], v[146:149], v[178:181], 0
	v_mfma_f32_16x16x32_bf16 v[82:85], v[154:157], v[178:181], 0
	v_mfma_f32_16x16x32_bf16 v[70:73], v[146:149], v[204:207], 0
	v_mfma_f32_16x16x32_bf16 v[66:69], v[154:157], v[204:207], 0
	v_mfma_f32_16x16x32_bf16 v[118:121], v[150:153], v[166:169], v[118:121]
	v_mfma_f32_16x16x32_bf16 v[114:117], v[158:161], v[166:169], v[114:117]
	v_mfma_f32_16x16x32_bf16 v[102:105], v[150:153], v[174:177], v[102:105]
	v_mfma_f32_16x16x32_bf16 v[98:101], v[158:161], v[174:177], v[98:101]
	v_mfma_f32_16x16x32_bf16 v[86:89], v[150:153], v[182:185], v[86:89]
	v_mfma_f32_16x16x32_bf16 v[82:85], v[158:161], v[182:185], v[82:85]
	v_mfma_f32_16x16x32_bf16 v[70:73], v[150:153], v[208:211], v[70:73]
	v_mfma_f32_16x16x32_bf16 v[66:69], v[158:161], v[208:211], v[66:69]
	s_setprio 0
	s_barrier
	s_add_i32 s75, s52, s25
	v_lshl_add_u64 v[212:213], s[20:21], 0, v[188:189]
	s_mov_b32 m0, s75
	ds_read_b128 v[162:165], v220 offset:16384
	ds_read_b128 v[166:169], v220 offset:17408
	ds_read_b128 v[170:173], v220 offset:18432
	ds_read_b128 v[174:177], v220 offset:19456
	ds_read_b128 v[178:181], v220 offset:20480
	ds_read_b128 v[182:185], v220 offset:21504
	ds_read_b128 v[204:207], v220 offset:22528
	ds_read_b128 v[208:211], v220 offset:23552
	global_load_lds_dwordx4 v[212:213], off
	s_add_i32 m0, s75, 0x2000
	s_add_u32 s76, s20, 0x40000
	v_lshl_add_u64 v[214:215], s[20:21], 0, v[192:193]
	s_addc_u32 s77, s21, 0
	s_add_i32 s75, s53, s25
	global_load_lds_dwordx4 v[214:215], off
	v_lshl_add_u64 v[222:223], s[76:77], 0, v[188:189]
	s_mov_b32 m0, s75
	v_lshl_add_u64 v[224:225], s[66:67], 0, v[190:191]
	global_load_lds_dwordx4 v[222:223], off
	v_lshl_add_u64 v[222:223], s[76:77], 0, v[192:193]
	s_add_i32 m0, s75, 0x2000
	s_nop 0
	global_load_lds_dwordx4 v[222:223], off
	v_lshl_add_u64 v[222:223], s[66:67], 0, v[186:187]
	s_mov_b32 m0, s26
	s_nop 0
	global_load_lds_dwordx4 v[222:223], off
	s_mov_b32 m0, s27
	s_nop 0
	global_load_lds_dwordx4 v[224:225], off
	s_waitcnt vmcnt(8)
	s_waitcnt lgkmcnt(0)
	s_barrier
	s_setprio 1
	s_waitcnt lgkmcnt(0)
	v_mfma_f32_16x16x32_bf16 v[62:65], v[130:133], v[162:165], 0
	v_mfma_f32_16x16x32_bf16 v[58:61], v[138:141], v[162:165], 0
	v_mfma_f32_16x16x32_bf16 v[46:49], v[130:133], v[170:173], 0
	v_mfma_f32_16x16x32_bf16 v[42:45], v[138:141], v[170:173], 0
	v_mfma_f32_16x16x32_bf16 v[30:33], v[130:133], v[178:181], 0
	v_mfma_f32_16x16x32_bf16 v[26:29], v[138:141], v[178:181], 0
	v_mfma_f32_16x16x32_bf16 v[14:17], v[130:133], v[204:207], 0
	v_mfma_f32_16x16x32_bf16 v[10:13], v[138:141], v[204:207], 0
	v_mfma_f32_16x16x32_bf16 v[62:65], v[134:137], v[166:169], v[62:65]
	v_mfma_f32_16x16x32_bf16 v[58:61], v[142:145], v[166:169], v[58:61]
	v_mfma_f32_16x16x32_bf16 v[46:49], v[134:137], v[174:177], v[46:49]
	v_mfma_f32_16x16x32_bf16 v[42:45], v[142:145], v[174:177], v[42:45]
	v_mfma_f32_16x16x32_bf16 v[30:33], v[134:137], v[182:185], v[30:33]
	v_mfma_f32_16x16x32_bf16 v[26:29], v[142:145], v[182:185], v[26:29]
	v_mfma_f32_16x16x32_bf16 v[14:17], v[134:137], v[208:211], v[14:17]
	v_mfma_f32_16x16x32_bf16 v[10:13], v[142:145], v[208:211], v[10:13]
	s_setprio 0
	s_setprio 1
	v_mfma_f32_16x16x32_bf16 v[54:57], v[146:149], v[162:165], 0
	v_mfma_f32_16x16x32_bf16 v[50:53], v[154:157], v[162:165], 0
	v_mfma_f32_16x16x32_bf16 v[38:41], v[146:149], v[170:173], 0
	v_mfma_f32_16x16x32_bf16 v[34:37], v[154:157], v[170:173], 0
	v_mfma_f32_16x16x32_bf16 v[22:25], v[146:149], v[178:181], 0
	v_mfma_f32_16x16x32_bf16 v[18:21], v[154:157], v[178:181], 0
	v_mfma_f32_16x16x32_bf16 v[6:9], v[146:149], v[204:207], 0
	v_mfma_f32_16x16x32_bf16 v[2:5], v[154:157], v[204:207], 0
	v_mfma_f32_16x16x32_bf16 v[54:57], v[150:153], v[166:169], v[54:57]
	v_mfma_f32_16x16x32_bf16 v[50:53], v[158:161], v[166:169], v[50:53]
	v_mfma_f32_16x16x32_bf16 v[38:41], v[150:153], v[174:177], v[38:41]
	v_mfma_f32_16x16x32_bf16 v[34:37], v[158:161], v[174:177], v[34:37]
	v_mfma_f32_16x16x32_bf16 v[22:25], v[150:153], v[182:185], v[22:25]
	v_mfma_f32_16x16x32_bf16 v[18:21], v[158:161], v[182:185], v[18:21]
	v_mfma_f32_16x16x32_bf16 v[6:9], v[150:153], v[208:211], v[6:9]
	v_mfma_f32_16x16x32_bf16 v[2:5], v[158:161], v[208:211], v[2:5]
	s_setprio 0
	s_barrier
	s_branch .Lmid_P4

; #define PG8_STAGE(bufoff, gbase, voff) do { _Pragma("unroll") for (int _i = 0; _i < 2; ++_i) \
;         __builtin_amdgcn_global_load_lds((const unsigned*)((const char*)(gbase) + (voff)[_i]), (LAS unsigned*)(lds + (bufoff) + ldsw + _i * 8192), 16, 0, 0); } while (0)
; #define PG8_LDA(dst, b, h) do { _Pragma("unroll") for (int m = 0; m < 4; ++m) _Pragma("unroll") for (int k = 0; k < 2; ++k) dst[m][k] = *(const LAS bf16x8*)(lds + PG8_SA(b, h) + aoff + m * 2048 + k * 1024); } while (0)
; #define PG8_LDB(dst, b, h) do { _Pragma("unroll") for (int n = 0; n < 2; ++n) _Pragma("unroll") for (int k = 0; k < 2; ++k) dst[n][k] = *(const LAS bf16x8*)(lds + PG8_SB(b, h) + boff + n * 2048 + k * 1024); } while (0)
; #define PG8_MMA(ai, bj, At, Bt) do { __builtin_amdgcn_s_setprio(1); _Pragma("unroll") for (int m = 0; m < 4; ++m) _Pragma("unroll") for (int n = 0; n < 2; ++n) _Pragma("unroll") for (int k = 0; k < 2; ++k) \
;         acc[ai][bj][m][n] = __builtin_amdgcn_mfma_f32_16x16x32_bf16(Bt[n][k], At[m][k], acc[ai][bj][m][n], 0, 0, 0); __builtin_amdgcn_s_setprio(0); } while (0)
; #define PG8_WAIT_V(n) asm volatile("s_waitcnt vmcnt(" #n ")" ::: "memory")
; #define PG8_WAIT_L(n) asm volatile("s_waitcnt lgkmcnt(" #n ")" ::: "memory")
; #define PG8_BAR __builtin_amdgcn_s_barrier()
; #define PG8_SCHED __builtin_amdgcn_sched_barrier(0)
; template <class Epi, int AC0, int BC0, int NT0, int AC1, int BC1, int NT1>
; __device__ __forceinline__ void gemm_phase(LAS unsigned char* lds, const Gemm g, const StaticOrder& S, const Epi& E, int tid) {
;     ...
;             PG8_LDB(B0, 0, 0); PG8_LDB(B1, 0, 1); PG8_SCHED; PG8_LDA(At, 0, 0); PG8_STAGE(PG8_SA(1, 1), a1 + hstepA, voffA);
;             PG8_WAIT_V(8); PG8_WAIT_L(0); PG8_BAR; PG8_MMA(0, 0, At, B0); PG8_MMA(0, 1, At, B1); PG8_BAR; PG8_SCHED;
;             PG8_LDA(At, 0, 1); PG8_STAGE(PG8_SB(0, 0), b2, voffB); PG8_STAGE(PG8_SB(0, 1), b2 + hstepB, voffB); PG8_STAGE(PG8_SA(0, 0), a2, voffA);
;             PG8_WAIT_V(8); PG8_WAIT_L(0); PG8_BAR; PG8_MMA(1, 0, At, B0); PG8_MMA(1, 1, At, B1); PG8_BAR; PG8_SCHED;
.Lpeel_P5:
	ds_read_b128 v[128:131], v231
	ds_read_b128 v[132:135], v231 offset:1024
	ds_read_b128 v[136:139], v231 offset:2048
	ds_read_b128 v[140:143], v231 offset:3072
	ds_read_b128 v[144:147], v232
	ds_read_b128 v[148:151], v232 offset:1024
	ds_read_b128 v[152:155], v232 offset:2048
	ds_read_b128 v[156:159], v232 offset:3072
	s_add_u32 s20, s18, 0x100
	s_addc_u32 s21, s19, 0
	s_cmp_eq_u32 s33, s50
	s_cselect_b32 s25, s5, s21
	s_cselect_b32 s24, s4, s20
	s_cselect_b32 s23, s15, s47
	s_cselect_b32 s22, s14, s46
	v_lshl_add_u64 v[206:207], s[18:19], 0, v[200:201]
	s_add_i32 m0, s28, 0xc000
	ds_read_b128 v[160:163], v233
	ds_read_b128 v[164:167], v233 offset:1024
	ds_read_b128 v[168:171], v233 offset:2048
	ds_read_b128 v[172:175], v233 offset:3072
	ds_read_b128 v[176:179], v233 offset:4096
	ds_read_b128 v[180:183], v233 offset:5120
	ds_read_b128 v[184:187], v233 offset:6144
	ds_read_b128 v[188:191], v233 offset:7168
	global_load_lds_dwordx4 v[206:207], off
	v_lshl_add_u64 v[206:207], s[18:19], 0, v[202:203]
	s_add_i32 m0, s28, 0xe000
	s_nop 0
	global_load_lds_dwordx4 v[206:207], off
	s_waitcnt vmcnt(24)
	s_waitcnt lgkmcnt(0)
	s_barrier
	s_setprio 1
	s_waitcnt lgkmcnt(0)
	v_mfma_f32_16x16x32_bf16 v[124:127], v[128:131], v[160:163], 0
	v_mfma_f32_16x16x32_bf16 v[120:123], v[136:139], v[160:163], 0
	v_mfma_f32_16x16x32_bf16 v[116:119], v[128:131], v[168:171], 0
	v_mfma_f32_16x16x32_bf16 v[112:115], v[136:139], v[168:171], 0
	v_mfma_f32_16x16x32_bf16 v[100:103], v[128:131], v[176:179], 0
	v_mfma_f32_16x16x32_bf16 v[96:99], v[136:139], v[176:179], 0
	v_mfma_f32_16x16x32_bf16 v[84:87], v[128:131], v[184:187], 0
	v_mfma_f32_16x16x32_bf16 v[80:83], v[136:139], v[184:187], 0
	v_mfma_f32_16x16x32_bf16 v[124:127], v[132:135], v[164:167], v[124:127]
	v_mfma_f32_16x16x32_bf16 v[120:123], v[140:143], v[164:167], v[120:123]
	v_mfma_f32_16x16x32_bf16 v[116:119], v[132:135], v[172:175], v[116:119]
	v_mfma_f32_16x16x32_bf16 v[112:115], v[140:143], v[172:175], v[112:115]
	v_mfma_f32_16x16x32_bf16 v[100:103], v[132:135], v[180:183], v[100:103]
	v_mfma_f32_16x16x32_bf16 v[96:99], v[140:143], v[180:183], v[96:99]
	v_mfma_f32_16x16x32_bf16 v[84:87], v[132:135], v[188:191], v[84:87]
	v_mfma_f32_16x16x32_bf16 v[80:83], v[140:143], v[188:191], v[80:83]
	s_setprio 0
	s_setprio 1
	v_mfma_f32_16x16x32_bf16 v[108:111], v[144:147], v[160:163], 0
	v_mfma_f32_16x16x32_bf16 v[104:107], v[152:155], v[160:163], 0
	v_mfma_f32_16x16x32_bf16 v[92:95], v[144:147], v[168:171], 0
	v_mfma_f32_16x16x32_bf16 v[88:91], v[152:155], v[168:171], 0
	v_mfma_f32_16x16x32_bf16 v[76:79], v[144:147], v[176:179], 0
	v_mfma_f32_16x16x32_bf16 v[72:75], v[152:155], v[176:179], 0
	v_mfma_f32_16x16x32_bf16 v[68:71], v[144:147], v[184:187], 0
	v_mfma_f32_16x16x32_bf16 v[64:67], v[152:155], v[184:187], 0
	v_mfma_f32_16x16x32_bf16 v[108:111], v[148:151], v[164:167], v[108:111]
	v_mfma_f32_16x16x32_bf16 v[104:107], v[156:159], v[164:167], v[104:107]
	v_mfma_f32_16x16x32_bf16 v[92:95], v[148:151], v[172:175], v[92:95]
	v_mfma_f32_16x16x32_bf16 v[88:91], v[156:159], v[172:175], v[88:91]
	v_mfma_f32_16x16x32_bf16 v[76:79], v[148:151], v[180:183], v[76:79]
	v_mfma_f32_16x16x32_bf16 v[72:75], v[156:159], v[180:183], v[72:75]
	v_mfma_f32_16x16x32_bf16 v[68:71], v[148:151], v[188:191], v[68:71]
	v_mfma_f32_16x16x32_bf16 v[64:67], v[156:159], v[188:191], v[64:67]
	s_setprio 0
	s_barrier
	s_add_i32 s18, s37, s27
	v_lshl_add_u64 v[206:207], s[22:23], 0, v[194:195]
	s_mov_b32 m0, s18
	ds_read_b128 v[160:163], v233 offset:16384
	ds_read_b128 v[164:167], v233 offset:17408
	ds_read_b128 v[168:171], v233 offset:18432
	ds_read_b128 v[172:175], v233 offset:19456
	ds_read_b128 v[176:179], v233 offset:20480
	ds_read_b128 v[180:183], v233 offset:21504
	ds_read_b128 v[184:187], v233 offset:22528
	ds_read_b128 v[188:191], v233 offset:23552
	global_load_lds_dwordx4 v[206:207], off
	s_add_i32 m0, s18, 0x2000
	s_add_u32 s18, s22, 0x50000
	v_lshl_add_u64 v[208:209], s[22:23], 0, v[198:199]
	s_addc_u32 s19, s23, 0
	s_add_i32 s51, s38, s27
	global_load_lds_dwordx4 v[208:209], off
	v_lshl_add_u64 v[210:211], s[18:19], 0, v[194:195]
	s_mov_b32 m0, s51
	v_lshl_add_u64 v[212:213], s[24:25], 0, v[196:197]
	global_load_lds_dwordx4 v[210:211], off
	v_lshl_add_u64 v[210:211], s[18:19], 0, v[198:199]
	s_add_i32 m0, s51, 0x2000
	s_nop 0
	global_load_lds_dwordx4 v[210:211], off
	v_lshl_add_u64 v[210:211], s[24:25], 0, v[192:193]
	s_mov_b32 m0, s28
	s_nop 0
	global_load_lds_dwordx4 v[210:211], off
	s_mov_b32 m0, s29
	s_nop 0
	global_load_lds_dwordx4 v[212:213], off
	s_waitcnt vmcnt(8)
	s_waitcnt lgkmcnt(0)
	s_barrier
	s_setprio 1
	s_waitcnt lgkmcnt(0)
	v_mfma_f32_16x16x32_bf16 v[60:63], v[128:131], v[160:163], 0
	v_mfma_f32_16x16x32_bf16 v[56:59], v[136:139], v[160:163], 0
	v_mfma_f32_16x16x32_bf16 v[52:55], v[128:131], v[168:171], 0
	v_mfma_f32_16x16x32_bf16 v[48:51], v[136:139], v[168:171], 0
	v_mfma_f32_16x16x32_bf16 v[36:39], v[128:131], v[176:179], 0
	v_mfma_f32_16x16x32_bf16 v[32:35], v[136:139], v[176:179], 0
	v_mfma_f32_16x16x32_bf16 v[20:23], v[128:131], v[184:187], 0
	v_mfma_f32_16x16x32_bf16 v[16:19], v[136:139], v[184:187], 0
	v_mfma_f32_16x16x32_bf16 v[60:63], v[132:135], v[164:167], v[60:63]
	v_mfma_f32_16x16x32_bf16 v[56:59], v[140:143], v[164:167], v[56:59]
	v_mfma_f32_16x16x32_bf16 v[52:55], v[132:135], v[172:175], v[52:55]
	v_mfma_f32_16x16x32_bf16 v[48:51], v[140:143], v[172:175], v[48:51]
	v_mfma_f32_16x16x32_bf16 v[36:39], v[132:135], v[180:183], v[36:39]
	v_mfma_f32_16x16x32_bf16 v[32:35], v[140:143], v[180:183], v[32:35]
	v_mfma_f32_16x16x32_bf16 v[20:23], v[132:135], v[188:191], v[20:23]
	v_mfma_f32_16x16x32_bf16 v[16:19], v[140:143], v[188:191], v[16:19]
	s_setprio 0
	s_setprio 1
	v_mfma_f32_16x16x32_bf16 v[44:47], v[144:147], v[160:163], 0
	v_mfma_f32_16x16x32_bf16 v[40:43], v[152:155], v[160:163], 0
	v_mfma_f32_16x16x32_bf16 v[28:31], v[144:147], v[168:171], 0
	v_mfma_f32_16x16x32_bf16 v[24:27], v[152:155], v[168:171], 0
	v_mfma_f32_16x16x32_bf16 v[12:15], v[144:147], v[176:179], 0
	v_mfma_f32_16x16x32_bf16 v[8:11], v[152:155], v[176:179], 0
	v_mfma_f32_16x16x32_bf16 v[4:7], v[144:147], v[184:187], 0
	v_mfma_f32_16x16x32_bf16 v[0:3], v[152:155], v[184:187], 0
	v_mfma_f32_16x16x32_bf16 v[44:47], v[148:151], v[164:167], v[44:47]
	v_mfma_f32_16x16x32_bf16 v[40:43], v[156:159], v[164:167], v[40:43]
	v_mfma_f32_16x16x32_bf16 v[28:31], v[148:151], v[172:175], v[28:31]
	v_mfma_f32_16x16x32_bf16 v[24:27], v[156:159], v[172:175], v[24:27]
	v_mfma_f32_16x16x32_bf16 v[12:15], v[148:151], v[180:183], v[12:15]
	v_mfma_f32_16x16x32_bf16 v[8:11], v[156:159], v[180:183], v[8:11]
	v_mfma_f32_16x16x32_bf16 v[4:7], v[148:151], v[188:191], v[4:7]
	v_mfma_f32_16x16x32_bf16 v[0:3], v[156:159], v[188:191], v[0:3]
	s_setprio 0
	s_barrier
	s_branch .Lmid_P5
